# speedup vs baseline: 1.0135x; 1.0135x over previous
; #define MFMA(a, b, c) __builtin_amdgcn_mfma_f32_16x16x32_bf16(a, b, c, 0, 0, 0)
; __device__ __forceinline__ void attn_phase(const Params& p, int layer, char* smem) {
;     ...
;     for (int kt = 0; kt < nkt; ++kt) {
;       if (kt + 1 < nkt) gload(kt + 1);
;       const char* Ks = smem + (kt & 1) * 32768 + mm * 8192;
;       const char* Vs = smem + (kt & 1) * 32768 + 16384;
;       f32x4 st[2][4];
;       __builtin_amdgcn_s_setprio(1);
; #pragma unroll
;       for (int k4 = 0; k4 < 4; ++k4) {
;         const bf16x8 af0 = *(const bf16x8*)(Ks + sw128(k4 * 16 + fr, fq));
;         const bf16x8 af1 = *(const bf16x8*)(Ks + sw128(k4 * 16 + fr, 4 + fq));
;         const f32x4 z4 = {0.f, 0.f, 0.f, 0.f};
;         st[0][k4] = MFMA(af0, qf[0][0], z4);
;         st[1][k4] = MFMA(af0, qf[1][0], z4);
;         st[0][k4] = MFMA(af1, qf[0][1], st[0][k4]);
;         st[1][k4] = MFMA(af1, qf[1][1], st[1][k4]);
;       }
;       __builtin_amdgcn_s_setprio(0);
;       bf16x8 pb[2][2];
; #pragma unroll
;       for (int qt = 0; qt < 2; ++qt) {
;         float ls = 0.f;
; #pragma unroll
;         for (int k4 = 0; k4 < 4; ++k4)
; #pragma unroll
;           for (int j = 0; j < 4; ++j) {
;             float pe = __builtin_amdgcn_exp2f(st[qt][k4][j]);
;             st[qt][k4][j] = pe;
;             ls += pe;
;           }
;         lrun[qt] += ls;
; #pragma unroll
;         for (int k2 = 0; k2 < 2; ++k2) {
;           union { bf16x8 v; unsigned u[4]; } pk;
;           pk.u[0] = pack2(st[qt][k2 * 2][0], st[qt][k2 * 2][1]);
;           pk.u[1] = pack2(st[qt][k2 * 2][2], st[qt][k2 * 2][3]);
;           pk.u[2] = pack2(st[qt][k2 * 2 + 1][0], st[qt][k2 * 2 + 1][1]);
;           pk.u[3] = pack2(st[qt][k2 * 2 + 1][2], st[qt][k2 * 2 + 1][3]);
;           pb[qt][k2] = pk.v;
;         }
;       }
;       __builtin_amdgcn_s_setprio(1);
; #pragma unroll
;       for (int et = 0; et < 8; ++et)
; #pragma unroll
;         for (int k2 = 0; k2 < 2; ++k2) {
;           const bf16x8 av = *(const bf16x8*)(Vs + sw128(et * 16 + fr, k2 * 4 + fq));
;           o[0][et] = MFMA(av, pb[0][k2], o[0][et]);
;           o[1][et] = MFMA(av, pb[1][k2], o[1][et]);
;         }
.LBB0_498:
	v_lshl_add_u64 v[80:81], v[142:143], 0, v[152:153]
	s_mov_b32 s8, 0x12478000
	v_add_co_u32_e32 v84, vcc, s8, v80
	v_lshl_add_u64 v[92:93], v[142:143], 0, v[150:151]
	s_nop 0
	v_addc_co_u32_e32 v85, vcc, 0, v81, vcc
	s_mov_b32 s8, 0x2d418000
	v_add_co_u32_e32 v88, vcc, s8, v92
	s_mov_b32 s8, 0x2d460000
	s_nop 0
	v_addc_co_u32_e32 v89, vcc, 0, v93, vcc
	v_add_co_u32_e32 v92, vcc, s8, v92
	global_load_dwordx4 v[80:83], v[84:85], off offset:2048
	s_nop 0
	global_load_dwordx4 v[84:87], v[84:85], off offset:2176
	v_addc_co_u32_e32 v93, vcc, 0, v93, vcc
	global_load_dwordx4 v[88:91], v[88:89], off offset:128
	s_and_b32 s8, s45, 0x8000
	global_load_dwordx4 v[92:95], v[92:93], off offset:128
	s_addk_i32 s8, 0x190
	v_add_u32_e32 v169, s8, v159
	s_setprio 1
	v_add_u32_e32 v190, v169, v161
	ds_read_b128 v[170:173], v190
	ds_read_b128 v[174:177], v190 offset:2048
	v_add_u32_e32 v169, v169, v162
	ds_read_b128 v[182:185], v169
	ds_read_b128 v[186:189], v169 offset:2048
	s_waitcnt vmcnt(7) lgkmcnt(3)
	v_mfma_f32_16x16x32_bf16 v[178:181], v[170:173], v[56:59], 0
	s_waitcnt vmcnt(5)
	v_mfma_f32_16x16x32_bf16 v[170:173], v[170:173], v[60:63], 0
	s_waitcnt lgkmcnt(1)
	v_mfma_f32_16x16x32_bf16 v[178:181], v[182:185], v[44:47], v[178:181]
	s_waitcnt vmcnt(4)
	v_mfma_f32_16x16x32_bf16 v[170:173], v[182:185], v[48:51], v[170:173]
	v_mfma_f32_16x16x32_bf16 v[182:185], v[174:177], v[56:59], 0
	v_mfma_f32_16x16x32_bf16 v[174:177], v[174:177], v[60:63], 0
	s_waitcnt lgkmcnt(0)
	v_mfma_f32_16x16x32_bf16 v[182:185], v[186:189], v[44:47], v[182:185]
	v_mfma_f32_16x16x32_bf16 v[174:177], v[186:189], v[48:51], v[174:177]
	ds_read_b128 v[186:189], v190 offset:4096
	ds_read_b128 v[190:193], v190 offset:6144
	ds_read_b128 v[198:201], v169 offset:4096
	ds_read_b128 v[226:229], v169 offset:6144
	s_waitcnt lgkmcnt(3)
	v_mfma_f32_16x16x32_bf16 v[194:197], v[186:189], v[56:59], 0
	v_mfma_f32_16x16x32_bf16 v[186:189], v[186:189], v[60:63], 0
	s_waitcnt lgkmcnt(1)
	v_mfma_f32_16x16x32_bf16 v[194:197], v[198:201], v[44:47], v[194:197]
	v_mfma_f32_16x16x32_bf16 v[186:189], v[198:201], v[48:51], v[186:189]
	v_mfma_f32_16x16x32_bf16 v[198:201], v[190:193], v[56:59], 0
	v_mfma_f32_16x16x32_bf16 v[190:193], v[190:193], v[60:63], 0
	s_waitcnt lgkmcnt(0)
	v_mfma_f32_16x16x32_bf16 v[198:201], v[226:229], v[44:47], v[198:201]
	v_mfma_f32_16x16x32_bf16 v[190:193], v[226:229], v[48:51], v[190:193]
	s_setprio 0
	v_exp_f32_e32 v227, v178
	v_exp_f32_e32 v226, v170
	v_exp_f32_e32 v179, v179
	v_exp_f32_e32 v178, v171
	v_exp_f32_e32 v229, v180
	v_exp_f32_e32 v228, v172
	v_exp_f32_e32 v181, v181
	v_exp_f32_e32 v180, v173
	v_exp_f32_e32 v231, v182
	v_exp_f32_e32 v230, v174
	v_exp_f32_e32 v182, v175
	v_pk_add_f32 v[174:175], v[226:227], 0 op_sel_hi:[1,0]
	v_exp_f32_e32 v183, v183
	v_pk_add_f32 v[174:175], v[178:179], v[174:175]
	v_exp_f32_e32 v233, v184
	v_pk_add_f32 v[174:175], v[228:229], v[174:175]
	v_exp_f32_e32 v232, v176
	v_exp_f32_e32 v185, v185
	v_pk_add_f32 v[174:175], v[180:181], v[174:175]
	v_exp_f32_e32 v184, v177
	v_exp_f32_e32 v235, v194
	v_pk_add_f32 v[174:175], v[174:175], v[230:231]
	v_exp_f32_e32 v234, v186
	v_exp_f32_e32 v195, v195
	v_pk_add_f32 v[174:175], v[182:183], v[174:175]
	v_exp_f32_e32 v194, v187
	v_exp_f32_e32 v237, v196
	v_exp_f32_e32 v236, v188
	v_pk_add_f32 v[174:175], v[232:233], v[174:175]
	v_exp_f32_e32 v197, v197
	v_exp_f32_e32 v196, v189
	v_pk_add_f32 v[174:175], v[184:185], v[174:175]
	v_exp_f32_e32 v239, v198
	v_exp_f32_e32 v238, v190
	v_pk_add_f32 v[174:175], v[174:175], v[234:235]
	v_exp_f32_e32 v199, v199
	v_exp_f32_e32 v198, v191
	v_pk_add_f32 v[174:175], v[194:195], v[174:175]
	v_exp_f32_e32 v241, v200
	v_exp_f32_e32 v240, v192
	v_pk_add_f32 v[174:175], v[236:237], v[174:175]
	v_exp_f32_e32 v201, v201
	v_exp_f32_e32 v200, v193
	v_pk_add_f32 v[174:175], v[196:197], v[174:175]
	v_cvt_pk_bf16_f32 v170, v227, v179
	v_pk_add_f32 v[174:175], v[174:175], v[238:239]
	v_cvt_pk_bf16_f32 v171, v229, v181
	v_pk_add_f32 v[174:175], v[198:199], v[174:175]
	v_cvt_pk_bf16_f32 v172, v231, v183
	v_pk_add_f32 v[174:175], v[240:241], v[174:175]
	v_cvt_pk_bf16_f32 v173, v233, v185
	v_pk_add_f32 v[186:187], v[200:201], v[174:175]
	v_cvt_pk_bf16_f32 v174, v235, v195
	v_pk_add_f32 v[148:149], v[148:149], v[186:187]
	v_cvt_pk_bf16_f32 v175, v237, v197
	v_cvt_pk_bf16_f32 v176, v239, v199
	v_cvt_pk_bf16_f32 v177, v241, v201
	v_cvt_pk_bf16_f32 v178, v226, v178
	v_cvt_pk_bf16_f32 v179, v228, v180
	v_cvt_pk_bf16_f32 v180, v230, v182
	v_cvt_pk_bf16_f32 v181, v232, v184
	v_cvt_pk_bf16_f32 v182, v234, v194
	v_cvt_pk_bf16_f32 v183, v236, v196
	v_cvt_pk_bf16_f32 v184, v238, v198
	v_cvt_pk_bf16_f32 v185, v240, v200
	s_setprio 1
	v_add_u32_e32 v169, s8, v161
	v_add_u32_e32 v252, s8, v162
	ds_read_b128 v[186:189], v169 offset:16384
	ds_read_b128 v[244:247], v169 offset:18432
	ds_read_b128 v[248:251], v169 offset:20480
	s_waitcnt lgkmcnt(2)
	v_mfma_f32_16x16x32_bf16 v[76:79], v[186:189], v[170:173], v[76:79]
	v_mfma_f32_16x16x32_bf16 v[52:55], v[186:189], v[178:181], v[52:55]
	ds_read_b128 v[186:189], v169 offset:22528
	s_waitcnt lgkmcnt(2)
	v_mfma_f32_16x16x32_bf16 v[72:75], v[244:247], v[170:173], v[72:75]
	v_mfma_f32_16x16x32_bf16 v[36:39], v[244:247], v[178:181], v[36:39]
	ds_read_b128 v[244:247], v169 offset:24576
	s_waitcnt lgkmcnt(2)
	v_mfma_f32_16x16x32_bf16 v[68:71], v[248:251], v[170:173], v[68:71]
	v_mfma_f32_16x16x32_bf16 v[28:31], v[248:251], v[178:181], v[28:31]
	ds_read_b128 v[248:251], v169 offset:26624
	s_waitcnt lgkmcnt(2)
	v_mfma_f32_16x16x32_bf16 v[64:67], v[186:189], v[170:173], v[64:67]
	v_mfma_f32_16x16x32_bf16 v[24:27], v[186:189], v[178:181], v[24:27]
	ds_read_b128 v[186:189], v169 offset:28672
	s_waitcnt lgkmcnt(2)
; #define MFMA(a, b, c) __builtin_amdgcn_mfma_f32_16x16x32_bf16(a, b, c, 0, 0, 0)
; __device__ __forceinline__ void attn_phase(const Params& p, int layer, char* smem) {
;     ...
; #pragma unroll
;       for (int k4 = 0; k4 < 4; ++k4) {
;         const bf16x8 af0 = *(const bf16x8*)(Ks + sw128(k4 * 16 + fr, fq));
;         const bf16x8 af1 = *(const bf16x8*)(Ks + sw128(k4 * 16 + fr, 4 + fq));
;         const f32x4 z4 = {0.f, 0.f, 0.f, 0.f};
;         st[0][k4] = MFMA(af0, qf[0][0], z4);
;         st[1][k4] = MFMA(af0, qf[1][0], z4);
;         st[0][k4] = MFMA(af1, qf[0][1], st[0][k4]);
;         st[1][k4] = MFMA(af1, qf[1][1], st[1][k4]);
;       }
;     ...
;       __builtin_amdgcn_s_setprio(1);
; #pragma unroll
;       for (int et = 0; et < 8; ++et)
; #pragma unroll
;         for (int k2 = 0; k2 < 2; ++k2) {
;           const bf16x8 av = *(const bf16x8*)(Vs + sw128(et * 16 + fr, k2 * 4 + fq));
;           o[0][et] = MFMA(av, pb[0][k2], o[0][et]);
;           o[1][et] = MFMA(av, pb[1][k2], o[1][et]);
;         }
;       __builtin_amdgcn_s_setprio(0);
;       if (kt + 1 < nkt) sstore((kt + 1) & 1);
;       __syncthreads();
	v_mfma_f32_16x16x32_bf16 v[40:43], v[244:247], v[170:173], v[40:43]
	v_mfma_f32_16x16x32_bf16 v[20:23], v[244:247], v[178:181], v[20:23]
	ds_read_b128 v[244:247], v169 offset:30720
	s_waitcnt lgkmcnt(2)
	v_mfma_f32_16x16x32_bf16 v[32:35], v[248:251], v[170:173], v[32:35]
	v_mfma_f32_16x16x32_bf16 v[16:19], v[248:251], v[178:181], v[16:19]
	ds_read_b128 v[248:251], v252 offset:16384
	s_waitcnt lgkmcnt(2)
	v_mfma_f32_16x16x32_bf16 v[12:15], v[186:189], v[170:173], v[12:15]
	v_mfma_f32_16x16x32_bf16 v[4:7], v[186:189], v[178:181], v[4:7]
	ds_read_b128 v[186:189], v252 offset:18432
	s_waitcnt lgkmcnt(2)
	v_mfma_f32_16x16x32_bf16 v[8:11], v[244:247], v[170:173], v[8:11]
	v_mfma_f32_16x16x32_bf16 v[0:3], v[244:247], v[178:181], v[0:3]
	ds_read_b128 v[244:247], v252 offset:20480
	s_waitcnt lgkmcnt(2)
	v_mfma_f32_16x16x32_bf16 v[76:79], v[248:251], v[174:177], v[76:79]
	v_mfma_f32_16x16x32_bf16 v[52:55], v[248:251], v[182:185], v[52:55]
	ds_read_b128 v[248:251], v252 offset:22528
	s_waitcnt lgkmcnt(2)
	v_mfma_f32_16x16x32_bf16 v[72:75], v[186:189], v[174:177], v[72:75]
	v_mfma_f32_16x16x32_bf16 v[36:39], v[186:189], v[182:185], v[36:39]
	ds_read_b128 v[186:189], v252 offset:24576
	s_waitcnt lgkmcnt(2)
	v_mfma_f32_16x16x32_bf16 v[68:71], v[244:247], v[174:177], v[68:71]
	v_mfma_f32_16x16x32_bf16 v[28:31], v[244:247], v[182:185], v[28:31]
	ds_read_b128 v[244:247], v252 offset:26624
	s_waitcnt lgkmcnt(2)
	v_mfma_f32_16x16x32_bf16 v[64:67], v[248:251], v[174:177], v[64:67]
	v_mfma_f32_16x16x32_bf16 v[24:27], v[248:251], v[182:185], v[24:27]
	ds_read_b128 v[248:251], v252 offset:28672
	s_waitcnt lgkmcnt(2)
	v_mfma_f32_16x16x32_bf16 v[40:43], v[186:189], v[174:177], v[40:43]
	v_mfma_f32_16x16x32_bf16 v[20:23], v[186:189], v[182:185], v[20:23]
	ds_read_b128 v[186:189], v252 offset:30720
	s_waitcnt lgkmcnt(2)
	v_mfma_f32_16x16x32_bf16 v[32:35], v[244:247], v[174:177], v[32:35]
	v_mfma_f32_16x16x32_bf16 v[16:19], v[244:247], v[182:185], v[16:19]
	s_waitcnt lgkmcnt(1)
	v_mfma_f32_16x16x32_bf16 v[12:15], v[248:251], v[174:177], v[12:15]
	v_mfma_f32_16x16x32_bf16 v[4:7], v[248:251], v[182:185], v[4:7]
	s_waitcnt lgkmcnt(0)
	v_mfma_f32_16x16x32_bf16 v[8:11], v[186:189], v[174:177], v[8:11]
	v_mfma_f32_16x16x32_bf16 v[0:3], v[186:189], v[182:185], v[0:3]
	s_setprio 0
	s_add_i32 s45, s45, 0x8000
	s_and_b32 s8, s45, 0x8000
	s_addk_i32 s8, 0x190
	v_add_u32_e32 v169, s8, v155
	s_mov_b64 s[46:47], 0x60000
	s_waitcnt vmcnt(3)
	ds_write_b128 v169, v[80:83]
	s_waitcnt vmcnt(2)
	ds_write_b128 v169, v[84:87] offset:8192
	v_add3_u32 v80, s8, v157, v156
	v_add3_u32 v81, s8, v158, v156
	v_lshl_add_u64 v[150:151], v[150:151], 0, s[48:49]
	s_cmp_lg_u32 s26, s45
	v_lshl_add_u64 v[152:153], v[152:153], 0, s[46:47]
	s_waitcnt vmcnt(1)
	ds_write_b64 v80, v[88:89] offset:16384
	ds_write_b64 v81, v[90:91] offset:16384
	s_waitcnt vmcnt(0)
	ds_write_b64 v80, v[92:93] offset:24576
	ds_write_b64 v81, v[94:95] offset:24576
	s_waitcnt lgkmcnt(0)
	s_barrier
	s_cbranch_scc1 .LBB0_498
	v_add_u32_e32 v88, s8, v159
	s_setprio 1
	v_add_u32_e32 v169, v88, v161
	ds_read_b128 v[80:83], v169
	v_add_u32_e32 v178, v88, v162
	ds_read_b128 v[88:91], v178
	s_waitcnt lgkmcnt(1)
	v_mfma_f32_16x16x32_bf16 v[84:87], v[80:83], v[56:59], 0
	ds_read_b128 v[150:153], v178 offset:2048
	ds_read_b128 v[174:177], v178 offset:4096
	v_mfma_f32_16x16x32_bf16 v[80:83], v[80:83], v[60:63], 0
	s_waitcnt lgkmcnt(2)
	v_mfma_f32_16x16x32_bf16 v[84:87], v[88:91], v[44:47], v[84:87]
	v_mfma_f32_16x16x32_bf16 v[80:83], v[88:91], v[48:51], v[80:83]
	ds_read_b128 v[88:91], v169 offset:2048
	s_waitcnt lgkmcnt(0)
	v_mfma_f32_16x16x32_bf16 v[92:95], v[88:91], v[56:59], 0
	v_mfma_f32_16x16x32_bf16 v[88:91], v[88:91], v[60:63], 0
	v_mfma_f32_16x16x32_bf16 v[92:95], v[150:153], v[44:47], v[92:95]
	v_mfma_f32_16x16x32_bf16 v[88:91], v[150:153], v[48:51], v[88:91]
	ds_read_b128 v[150:153], v169 offset:4096
	s_waitcnt lgkmcnt(0)
	v_mfma_f32_16x16x32_bf16 v[170:173], v[150:153], v[56:59], 0
	v_mfma_f32_16x16x32_bf16 v[150:153], v[150:153], v[60:63], 0
	v_mfma_f32_16x16x32_bf16 v[170:173], v[174:177], v[44:47], v[170:173]
	v_mfma_f32_16x16x32_bf16 v[150:153], v[174:177], v[48:51], v[150:153]
	ds_read_b128 v[174:177], v169 offset:6144
	s_waitcnt lgkmcnt(0)
	v_mfma_f32_16x16x32_bf16 v[56:59], v[174:177], v[56:59], 0
	v_mfma_f32_16x16x32_bf16 v[60:63], v[174:177], v[60:63], 0
	ds_read_b128 v[174:177], v178 offset:6144
	s_waitcnt lgkmcnt(0)
; #define MFMA(a, b, c) __builtin_amdgcn_mfma_f32_16x16x32_bf16(a, b, c, 0, 0, 0)
; __device__ __forceinline__ void attn_phase(const Params& p, int layer, char* smem) {
;     ...
;       bf16x8 pb[2][2];
; #pragma unroll
;       for (int qt = 0; qt < 2; ++qt) {
;         float ls = 0.f;
; #pragma unroll
;         for (int k4 = 0; k4 < 4; ++k4)
; #pragma unroll
;           for (int j = 0; j < 4; ++j) {
;             float pe = __builtin_amdgcn_exp2f(st[qt][k4][j]);
;             st[qt][k4][j] = pe;
;             ls += pe;
;           }
;         lrun[qt] += ls;
; #pragma unroll
;         for (int k2 = 0; k2 < 2; ++k2) {
;           union { bf16x8 v; unsigned u[4]; } pk;
;           pk.u[0] = pack2(st[qt][k2 * 2][0], st[qt][k2 * 2][1]);
;           pk.u[1] = pack2(st[qt][k2 * 2][2], st[qt][k2 * 2][3]);
;           pk.u[2] = pack2(st[qt][k2 * 2 + 1][0], st[qt][k2 * 2 + 1][1]);
;           pk.u[3] = pack2(st[qt][k2 * 2 + 1][2], st[qt][k2 * 2 + 1][3]);
;           pb[qt][k2] = pk.v;
;         }
;       }
;       __builtin_amdgcn_s_setprio(1);
; #pragma unroll
;       for (int et = 0; et < 8; ++et)
; #pragma unroll
;         for (int k2 = 0; k2 < 2; ++k2) {
;           const bf16x8 av = *(const bf16x8*)(Vs + sw128(et * 16 + fr, k2 * 4 + fq));
;           o[0][et] = MFMA(av, pb[0][k2], o[0][et]);
;           o[1][et] = MFMA(av, pb[1][k2], o[1][et]);
;         }
;       __builtin_amdgcn_s_setprio(0);
;       if (kt + 1 < nkt) sstore((kt + 1) & 1);
;       __syncthreads();
;     }
; #pragma unroll
;     for (int qt = 0; qt < 2; ++qt) {
;       float lt = lrun[qt];
;       lt += __shfl_xor(lt, 16);
;       lt += __shfl_xor(lt, 32);
	v_mfma_f32_16x16x32_bf16 v[44:47], v[174:177], v[44:47], v[56:59]
	v_mfma_f32_16x16x32_bf16 v[60:63], v[174:177], v[48:51], v[60:63]
	s_setprio 0
	v_exp_f32_e32 v48, v84
	v_exp_f32_e32 v49, v85
	v_exp_f32_e32 v50, v86
	v_exp_f32_e32 v51, v87
	v_add_f32_e32 v56, 0, v48
	v_exp_f32_e32 v58, v92
	v_add_f32_e32 v56, v49, v56
	v_exp_f32_e32 v59, v93
	v_add_f32_e32 v56, v50, v56
	v_exp_f32_e32 v84, v94
	v_add_f32_e32 v56, v51, v56
	v_exp_f32_e32 v85, v95
	v_add_f32_e32 v56, v56, v58
	v_exp_f32_e32 v86, v170
	v_add_f32_e32 v56, v59, v56
	v_exp_f32_e32 v87, v171
	v_add_f32_e32 v56, v84, v56
	v_exp_f32_e32 v92, v172
	v_add_f32_e32 v56, v85, v56
	v_exp_f32_e32 v93, v173
	v_add_f32_e32 v56, v56, v86
	v_exp_f32_e32 v44, v44
	v_exp_f32_e32 v45, v45
	v_add_f32_e32 v56, v87, v56
	v_add_f32_e32 v56, v92, v56
	v_exp_f32_e32 v46, v46
	v_exp_f32_e32 v47, v47
	v_add_f32_e32 v56, v93, v56
	v_add_f32_e32 v56, v56, v44
	v_cvt_pk_bf16_f32 v57, v50, v51
	v_cvt_pk_bf16_f32 v50, v44, v45
	v_exp_f32_e32 v44, v80
	v_add_f32_e32 v56, v45, v56
	v_exp_f32_e32 v45, v81
	v_add_f32_e32 v56, v46, v56
	v_cvt_pk_bf16_f32 v51, v46, v47
	v_exp_f32_e32 v46, v82
	v_add_f32_e32 v56, v47, v56
	v_exp_f32_e32 v47, v83
	v_add_f32_e32 v80, 0, v44
	v_exp_f32_e32 v81, v88
	v_add_f32_e32 v80, v45, v80
	v_exp_f32_e32 v82, v89
	v_add_f32_e32 v80, v46, v80
	v_exp_f32_e32 v83, v90
	v_cvt_pk_bf16_f32 v58, v58, v59
	v_cvt_pk_bf16_f32 v59, v84, v85
	v_add_f32_e32 v80, v47, v80
	v_exp_f32_e32 v84, v91
	v_add_f32_e32 v80, v80, v81
	v_exp_f32_e32 v85, v150
	v_add_f32_e32 v169, v149, v56
	v_cvt_pk_bf16_f32 v56, v48, v49
	v_cvt_pk_bf16_f32 v48, v86, v87
	v_add_f32_e32 v80, v82, v80
	v_exp_f32_e32 v86, v151
	v_add_f32_e32 v80, v83, v80
	v_exp_f32_e32 v87, v152
	v_add_f32_e32 v80, v84, v80
	v_exp_f32_e32 v88, v153
	v_add_f32_e32 v80, v80, v85
	v_exp_f32_e32 v89, v60
	v_add_f32_e32 v80, v86, v80
	v_exp_f32_e32 v90, v61
	v_add_f32_e32 v80, v87, v80
	v_exp_f32_e32 v91, v62
	v_cvt_pk_bf16_f32 v49, v92, v93
	v_add_f32_e32 v80, v88, v80
	v_exp_f32_e32 v92, v63
	v_add_f32_e32 v60, v80, v89
	v_add_f32_e32 v60, v90, v60
	v_add_f32_e32 v60, v91, v60
	v_add_f32_e32 v60, v92, v60
	v_add_f32_e32 v152, v148, v60
	v_cvt_pk_bf16_f32 v60, v44, v45
	v_cvt_pk_bf16_f32 v61, v46, v47
	v_cvt_pk_bf16_f32 v62, v81, v82
	v_cvt_pk_bf16_f32 v63, v83, v84
	v_cvt_pk_bf16_f32 v80, v85, v86
	v_cvt_pk_bf16_f32 v81, v87, v88
	v_cvt_pk_bf16_f32 v82, v89, v90
	v_cvt_pk_bf16_f32 v83, v91, v92
	s_setprio 1
	v_add_u32_e32 v153, s8, v161
	ds_read_b128 v[44:47], v153 offset:16384
	v_add_u32_e32 v170, s8, v162
	s_waitcnt lgkmcnt(0)
	v_mfma_f32_16x16x32_bf16 v[76:79], v[44:47], v[56:59], v[76:79]
	v_mfma_f32_16x16x32_bf16 v[44:47], v[44:47], v[60:63], v[52:55]
	s_nop 2
	ds_read_b128 v[52:55], v170 offset:16384
	s_waitcnt lgkmcnt(0)
	v_mfma_f32_16x16x32_bf16 v[76:79], v[52:55], v[48:51], v[76:79]
	v_mfma_f32_16x16x32_bf16 v[44:47], v[52:55], v[80:83], v[44:47]
	ds_read_b128 v[52:55], v153 offset:18432
	s_waitcnt lgkmcnt(0)
	v_mfma_f32_16x16x32_bf16 v[72:75], v[52:55], v[56:59], v[72:75]
	v_mfma_f32_16x16x32_bf16 v[36:39], v[52:55], v[60:63], v[36:39]
	ds_read_b128 v[52:55], v170 offset:18432
	s_waitcnt lgkmcnt(0)
	v_mfma_f32_16x16x32_bf16 v[72:75], v[52:55], v[48:51], v[72:75]
	v_mfma_f32_16x16x32_bf16 v[36:39], v[52:55], v[80:83], v[36:39]
	ds_read_b128 v[52:55], v153 offset:20480
	s_waitcnt lgkmcnt(0)
	v_mfma_f32_16x16x32_bf16 v[68:71], v[52:55], v[56:59], v[68:71]
	v_mfma_f32_16x16x32_bf16 v[28:31], v[52:55], v[60:63], v[28:31]
	ds_read_b128 v[52:55], v170 offset:20480
	s_waitcnt lgkmcnt(0)
	v_mfma_f32_16x16x32_bf16 v[68:71], v[52:55], v[48:51], v[68:71]
	v_mfma_f32_16x16x32_bf16 v[52:55], v[52:55], v[80:83], v[28:31]
	s_nop 3
	ds_read_b128 v[28:31], v153 offset:22528
	s_waitcnt lgkmcnt(0)
	v_mfma_f32_16x16x32_bf16 v[64:67], v[28:31], v[56:59], v[64:67]
	v_mfma_f32_16x16x32_bf16 v[24:27], v[28:31], v[60:63], v[24:27]
	ds_read_b128 v[28:31], v170 offset:22528
	s_waitcnt lgkmcnt(0)
	v_mfma_f32_16x16x32_bf16 v[84:87], v[28:31], v[80:83], v[24:27]
	s_nop 4
	ds_read_b128 v[24:27], v153 offset:24576
	v_mfma_f32_16x16x32_bf16 v[64:67], v[28:31], v[48:51], v[64:67]
	s_waitcnt lgkmcnt(0)
	v_mfma_f32_16x16x32_bf16 v[28:31], v[24:27], v[56:59], v[40:43]
	v_mfma_f32_16x16x32_bf16 v[20:23], v[24:27], v[60:63], v[20:23]
	ds_read_b128 v[24:27], v170 offset:24576
	s_waitcnt lgkmcnt(0)
	v_mfma_f32_16x16x32_bf16 v[88:91], v[24:27], v[80:83], v[20:23]
	s_nop 4
	ds_read_b128 v[20:23], v153 offset:26624
	v_mfma_f32_16x16x32_bf16 v[40:43], v[24:27], v[48:51], v[28:31]
	s_waitcnt lgkmcnt(0)
	v_mfma_f32_16x16x32_bf16 v[24:27], v[20:23], v[56:59], v[32:35]
	v_mfma_f32_16x16x32_bf16 v[16:19], v[20:23], v[60:63], v[16:19]
	ds_read_b128 v[20:23], v170 offset:26624
	s_waitcnt lgkmcnt(0)
	v_mfma_f32_16x16x32_bf16 v[92:95], v[20:23], v[80:83], v[16:19]
	s_nop 4
	ds_read_b128 v[16:19], v153 offset:28672
	s_waitcnt lgkmcnt(0)
	v_mfma_f32_16x16x32_bf16 v[12:15], v[16:19], v[56:59], v[12:15]
	v_mfma_f32_16x16x32_bf16 v[4:7], v[16:19], v[60:63], v[4:7]
	ds_read_b128 v[16:19], v170 offset:28672
	s_waitcnt lgkmcnt(0)
	v_mfma_f32_16x16x32_bf16 v[148:151], v[16:19], v[80:83], v[4:7]
	s_nop 4
	ds_read_b128 v[4:7], v153 offset:30720
	s_waitcnt lgkmcnt(0)
	v_mfma_f32_16x16x32_bf16 v[8:11], v[4:7], v[56:59], v[8:11]
	v_mfma_f32_16x16x32_bf16 v[0:3], v[4:7], v[60:63], v[0:3]
	ds_read_b128 v[4:7], v170 offset:30720
	v_mfma_f32_16x16x32_bf16 v[32:35], v[20:23], v[48:51], v[24:27]
	v_mfma_f32_16x16x32_bf16 v[12:15], v[16:19], v[48:51], v[12:15]
	s_waitcnt lgkmcnt(0)
	v_mfma_f32_16x16x32_bf16 v[8:11], v[4:7], v[48:51], v[8:11]
	v_mfma_f32_16x16x32_bf16 v[80:83], v[4:7], v[80:83], v[0:3]
	s_setprio 0
	s_nop 1
	ds_bpermute_b32 v0, v104, v169
	s_waitcnt lgkmcnt(0)
	s_barrier
; __device__ __forceinline__ void attn_phase(const Params& p, int layer, char* smem) {
;     ...
; #pragma unroll
;     for (int qt = 0; qt < 2; ++qt) {
;       float lt = lrun[qt];
;       lt += __shfl_xor(lt, 16);
;       lt += __shfl_xor(lt, 32);
;       float inv = 1.f / lt;
; #pragma unroll
;       for (int et = 0; et < 8; ++et) {
;         o[qt][et][0] *= inv; o[qt][et][1] *= inv; o[qt][et][2] *= inv; o[qt][et][3] *= inv;
;       }
;     }
;     if (mm == 1) {
; #pragma unroll
;       for (int qt = 0; qt < 2; ++qt)
; #pragma unroll
;         for (int et = 0; et < 8; ++et) {
;           int q = wq * 32 + qt * 16 + fr;
;           *(float4*)(comb + q * 128 + et * 16 + fq * 4) = float4{o[qt][et][0], o[qt][et][1], o[qt][et][2], o[qt][et][3]};
;         }
;     }
	v_add_f32_e32 v0, v169, v0
	ds_bpermute_b32 v1, v121, v0
	s_waitcnt lgkmcnt(0)
	v_add_f32_e32 v0, v0, v1
	v_div_scale_f32 v1, s[8:9], v0, v0, 1.0
	v_rcp_f32_e32 v2, v1
	v_div_scale_f32 v3, vcc, 1.0, v0, 1.0
	v_fma_f32 v4, -v1, v2, 1.0
	v_fmac_f32_e32 v2, v4, v2
	v_mul_f32_e32 v4, v3, v2
	v_fma_f32 v5, -v1, v4, v3
	v_fmac_f32_e32 v4, v5, v2
	v_fma_f32 v1, -v1, v4, v3
	v_div_fmas_f32 v1, v1, v2, v4
	v_div_fixup_f32 v0, v1, v0, 1.0
	v_mov_b32_e32 v2, v40
	v_mov_b32_e32 v3, v32
	v_pk_mul_f32 v[60:61], v[2:3], v[0:1] op_sel_hi:[1,0]
	v_mov_b32_e32 v32, v41
	v_mov_b32_e32 v2, v42
	v_mov_b32_e32 v3, v34
	v_pk_mul_f32 v[28:29], v[76:77], v[0:1] op_sel_hi:[1,0]
	v_pk_mul_f32 v[30:31], v[78:79], v[0:1] op_sel_hi:[1,0]
	v_pk_mul_f32 v[24:25], v[72:73], v[0:1] op_sel_hi:[1,0]
	v_pk_mul_f32 v[26:27], v[74:75], v[0:1] op_sel_hi:[1,0]
	v_pk_mul_f32 v[20:21], v[68:69], v[0:1] op_sel_hi:[1,0]
	v_pk_mul_f32 v[22:23], v[70:71], v[0:1] op_sel_hi:[1,0]
	v_pk_mul_f32 v[16:17], v[64:65], v[0:1] op_sel_hi:[1,0]
	v_pk_mul_f32 v[18:19], v[66:67], v[0:1] op_sel_hi:[1,0]
	v_pk_mul_f32 v[62:63], v[32:33], v[0:1] op_sel_hi:[1,0]
	v_pk_mul_f32 v[64:65], v[2:3], v[0:1] op_sel_hi:[1,0]
	ds_bpermute_b32 v1, v104, v152
	v_mov_b32_e32 v34, v43
	v_mov_b32_e32 v2, v12
	v_mov_b32_e32 v3, v8
	v_mov_b32_e32 v8, v13
	s_waitcnt lgkmcnt(0)
	v_pk_mul_f32 v[66:67], v[34:35], v[0:1] op_sel_hi:[1,0]
	v_pk_mul_f32 v[48:49], v[2:3], v[0:1] op_sel_hi:[1,0]
	v_add_f32_e32 v1, v152, v1
	ds_bpermute_b32 v4, v121, v1
	v_pk_mul_f32 v[50:51], v[8:9], v[0:1] op_sel_hi:[1,0]
	v_mov_b32_e32 v2, v14
	v_mov_b32_e32 v3, v10
	v_mov_b32_e32 v10, v15
	s_waitcnt lgkmcnt(0)
	v_add_f32_e32 v1, v1, v4
	v_div_scale_f32 v4, s[8:9], v1, v1, 1.0
	v_rcp_f32_e32 v5, v4
	v_pk_mul_f32 v[56:57], v[2:3], v[0:1] op_sel_hi:[1,0]
	v_pk_mul_f32 v[58:59], v[10:11], v[0:1] op_sel_hi:[1,0]
	v_mov_b32_e32 v32, v88
	v_fma_f32 v0, -v4, v5, 1.0
	v_fmac_f32_e32 v5, v0, v5
	v_div_scale_f32 v0, vcc, 1.0, v1, 1.0
	v_mul_f32_e32 v2, v0, v5
	v_fma_f32 v3, -v4, v2, v0
	v_fmac_f32_e32 v2, v3, v5
	v_fma_f32 v0, -v4, v2, v0
	v_div_fmas_f32 v0, v0, v5, v2
	v_div_fixup_f32 v68, v0, v1, 1.0
	v_pk_mul_f32 v[0:1], v[44:45], v[68:69] op_sel_hi:[1,0]
	v_pk_mul_f32 v[4:5], v[36:37], v[68:69] op_sel_hi:[1,0]
	v_mov_b32_e32 v33, v92
	v_mov_b32_e32 v92, v89
	v_mov_b32_e32 v36, v90
	v_mov_b32_e32 v37, v94
	v_mov_b32_e32 v94, v91
	v_mov_b32_e32 v40, v148
	v_mov_b32_e32 v41, v80
	v_mov_b32_e32 v80, v149
	v_mov_b32_e32 v44, v150
	v_mov_b32_e32 v45, v82
	v_mov_b32_e32 v82, v151
	v_pk_mul_f32 v[2:3], v[46:47], v[68:69] op_sel_hi:[1,0]
	v_pk_mul_f32 v[6:7], v[38:39], v[68:69] op_sel_hi:[1,0]
	v_pk_mul_f32 v[12:13], v[52:53], v[68:69] op_sel_hi:[1,0]
	v_pk_mul_f32 v[14:15], v[54:55], v[68:69] op_sel_hi:[1,0]
	v_pk_mul_f32 v[8:9], v[84:85], v[68:69] op_sel_hi:[1,0]
	v_pk_mul_f32 v[10:11], v[86:87], v[68:69] op_sel_hi:[1,0]
	v_pk_mul_f32 v[32:33], v[32:33], v[68:69] op_sel_hi:[1,0]
	v_pk_mul_f32 v[34:35], v[92:93], v[68:69] op_sel_hi:[1,0]
	v_pk_mul_f32 v[36:37], v[36:37], v[68:69] op_sel_hi:[1,0]
	v_pk_mul_f32 v[38:39], v[94:95], v[68:69] op_sel_hi:[1,0]
	v_pk_mul_f32 v[40:41], v[40:41], v[68:69] op_sel_hi:[1,0]
	v_pk_mul_f32 v[42:43], v[80:81], v[68:69] op_sel_hi:[1,0]
	v_pk_mul_f32 v[44:45], v[44:45], v[68:69] op_sel_hi:[1,0]
	v_pk_mul_f32 v[46:47], v[82:83], v[68:69] op_sel_hi:[1,0]
	s_and_saveexec_b64 s[8:9], s[0:1]
	s_cbranch_execz .LBB0_501
	v_mov_b32_e32 v52, v60
	v_mov_b32_e32 v53, v62
	v_mov_b32_e32 v54, v64
	v_mov_b32_e32 v55, v66
	ds_write_b128 v163, v[28:31]
	ds_write_b128 v163, v[24:27] offset:64
	ds_write_b128 v163, v[20:23] offset:128
	ds_write_b128 v163, v[16:19] offset:192
	ds_write_b128 v163, v[52:55] offset:256
	v_mov_b32_e32 v52, v61
	v_mov_b32_e32 v53, v63
	v_mov_b32_e32 v54, v65
	v_mov_b32_e32 v55, v67
	ds_write_b128 v163, v[52:55] offset:320
	v_mov_b32_e32 v52, v48
	v_mov_b32_e32 v53, v50
	v_mov_b32_e32 v54, v56
	v_mov_b32_e32 v55, v58
	ds_write_b128 v163, v[52:55] offset:384
	v_mov_b32_e32 v52, v49
	v_mov_b32_e32 v53, v51
	v_mov_b32_e32 v54, v57
	v_mov_b32_e32 v55, v59
	ds_write_b128 v163, v[52:55] offset:448
	ds_write_b128 v163, v[0:3] offset:8192
	ds_write_b128 v163, v[4:7] offset:8256
	ds_write_b128 v163, v[12:15] offset:8320
	ds_write_b128 v163, v[8:11] offset:8384
	v_mov_b32_e32 v52, v32
	v_mov_b32_e32 v53, v34
	v_mov_b32_e32 v54, v36
	v_mov_b32_e32 v55, v38
	ds_write_b128 v163, v[52:55] offset:8448
	v_mov_b32_e32 v52, v33
	v_mov_b32_e32 v53, v35
	v_mov_b32_e32 v54, v37
	v_mov_b32_e32 v55, v39
	ds_write_b128 v163, v[52:55] offset:8512
	v_mov_b32_e32 v52, v40
	v_mov_b32_e32 v53, v42
	v_mov_b32_e32 v54, v44
	v_mov_b32_e32 v55, v46
	ds_write_b128 v163, v[52:55] offset:8576
	v_mov_b32_e32 v52, v41
	v_mov_b32_e32 v53, v43
	v_mov_b32_e32 v54, v45
	v_mov_b32_e32 v55, v47
	ds_write_b128 v163, v[52:55] offset:8640

; __device__ __forceinline__ void rwkv_phase(const Params& p, int ei, char* smem) {
;     ...
;         for (int e = 0; e < 4; ++e) {
;           wq[e] = __expf(-0.6065306597126334f * sigm(w0v[e] + pwv[e]));
;           float a = sigm(a0v[e] + pav[e]);
;           kt[e] = val[1][e] * (1.f + (a - 1.f) * kav[e]);
;           akk[e] = a * kkn[e];
;           bsum += val[0][e] * kt[e] * rkv[e];
;         }
;         bsum = row_sum16(bsum);
;         if (l16 == 0) gst_f1(&bonus[row * 8 + h], bsum);
;         *(float4*)(OR + ti * 64 + c0) = float4{val[0][0], val[0][1], val[0][2], val[0][3]};
;         *(float4*)(OW + ti * 64 + c0) = float4{wq[0], wq[1], wq[2], wq[3]};
;         *(float4*)(OKT + ti * 64 + c0) = float4{kt[0], kt[1], kt[2], kt[3]};
;         *(float4*)(OV + ti * 64 + c0) = float4{val[2][0], val[2][1], val[2][2], val[2][3]};
;         *(float4*)(OKK + ti * 64 + c0) = float4{kkn[0], kkn[1], kkn[2], kkn[3]};
;         *(float4*)(OAKK + ti * 64 + c0) = float4{akk[0], akk[1], akk[2], akk[3]};
;       }
;       __syncthreads();
;     ...
;         for (int st = 0; st < 16; ++st) {
;           const float* ob = sOR + st * 64 + q * 16;
;           float kkv[16], wvv[16], akv[16], ktv[16], rv[16];
; #pragma unroll
;           for (int jj = 0; jj < 4; ++jj) {
;             float4 e = *(const float4*)(ob + jj * 4);
;             float4 bq = *(const float4*)(ob + 1024 + jj * 4);
;             float4 dd = *(const float4*)(ob + 2048 + jj * 4);
;             float4 a = *(const float4*)(ob + 4096 + jj * 4);
;             float4 c = *(const float4*)(ob + 5120 + jj * 4);
;             kkv[jj * 4] = a.x; kkv[jj * 4 + 1] = a.y; kkv[jj * 4 + 2] = a.z; kkv[jj * 4 + 3] = a.w;
;             wvv[jj * 4] = bq.x; wvv[jj * 4 + 1] = bq.y; wvv[jj * 4 + 2] = bq.z; wvv[jj * 4 + 3] = bq.w;
;             akv[jj * 4] = c.x; akv[jj * 4 + 1] = c.y; akv[jj * 4 + 2] = c.z; akv[jj * 4 + 3] = c.w;
;             ktv[jj * 4] = dd.x; ktv[jj * 4 + 1] = dd.y; ktv[jj * 4 + 2] = dd.z; ktv[jj * 4 + 3] = dd.w;
;             rv[jj * 4] = e.x; rv[jj * 4 + 1] = e.y; rv[jj * 4 + 2] = e.z; rv[jj * 4 + 3] = e.w;
;           }
;           const float v0 = sOR[3072 + st * 64 + rowv], v1 = sOR[3072 + st * 64 + rowv + 16];
;           float sa0 = 0.f, sa0b = 0.f, sa1 = 0.f, sa1b = 0.f;
; #pragma unroll
;           for (int j = 0; j < 16; j += 2) {
;             sa0 += S0[j] * kkv[j]; sa0b += S0[j + 1] * kkv[j + 1];
.LBB0_863:
	s_or_b64 exec, exec, s[44:45]
	v_cndmask_b32_e64 v104, v104, v198, s[14:15]
	v_cndmask_b32_e64 v104, v104, v199, s[16:17]
	v_mul_f32_e32 v198, 0x37800000, v104
	v_cndmask_b32_e32 v104, v104, v198, vcc
	v_mov_b32_e32 v198, 0x260
	v_cmp_class_f32_e32 vcc, v97, v198
	s_waitcnt lgkmcnt(0)
	v_add_f32_e32 v64, v24, v64
	v_add_f32_e32 v65, v25, v65
	v_cndmask_b32_e32 v97, v104, v97, vcc
	v_max_f32_e32 v97, 0x2b8cbccc, v97
	v_div_scale_f32 v104, s[14:15], v97, v97, 1.0
	v_rcp_f32_e32 v198, v104
	v_add_f32_e32 v66, v26, v66
	v_add_f32_e32 v67, v27, v67
	v_mul_f32_e32 v64, 0xbfb8aa3b, v64
	v_mul_f32_e32 v65, 0xbfb8aa3b, v65
	v_mul_f32_e32 v66, 0xbfb8aa3b, v66
	v_mul_f32_e32 v67, 0xbfb8aa3b, v67
	v_exp_f32_e32 v64, v64
	v_exp_f32_e32 v65, v65
	v_exp_f32_e32 v66, v66
	v_exp_f32_e32 v67, v67
	v_fma_f32 v199, -v104, v198, 1.0
	v_fmac_f32_e32 v198, v199, v198
	v_div_scale_f32 v199, vcc, 1.0, v97, 1.0
	v_mul_f32_e32 v200, v199, v198
	v_add_f32_e32 v64, 1.0, v64
	v_add_f32_e32 v65, 1.0, v65
	v_add_f32_e32 v66, 1.0, v66
	v_add_f32_e32 v67, 1.0, v67
	v_fma_f32 v201, -v104, v200, v199
	v_rcp_f32_e32 v64, v64
	v_rcp_f32_e32 v65, v65
	v_rcp_f32_e32 v66, v66
	v_rcp_f32_e32 v67, v67
	v_fmac_f32_e32 v200, v201, v198
	v_fma_f32 v104, -v104, v200, v199
	v_div_fmas_f32 v104, v104, v198, v200
	v_div_fixup_f32 v104, v104, v97, 1.0
	v_mul_f32_e32 v64, 0xbf1b4598, v64
	v_mul_f32_e32 v65, 0xbf1b4598, v65
	v_mul_f32_e32 v66, 0xbf1b4598, v66
	v_mul_f32_e32 v67, 0xbf1b4598, v67
	v_pk_mul_f32 v[200:201], v[190:191], v[104:105] op_sel_hi:[1,0]
	v_mul_f32_e32 v64, 0x3fb8aa3b, v64
	v_mul_f32_e32 v65, 0x3fb8aa3b, v65
	v_mul_f32_e32 v66, 0x3fb8aa3b, v66
	v_mul_f32_e32 v67, 0x3fb8aa3b, v67
	v_pk_mul_f32 v[198:199], v[192:193], v[104:105] op_sel_hi:[1,0]
	v_exp_f32_e32 v64, v64
	v_exp_f32_e32 v65, v65
	v_exp_f32_e32 v66, v66
	v_exp_f32_e32 v67, v67
	v_pk_mul_f32 v[192:193], v[200:201], v[196:197]
	v_lshlrev_b32_e32 v196, 16, v188
	v_and_b32_e32 v197, 0xffff0000, v188
	v_lshlrev_b32_e32 v188, 16, v189
	v_and_b32_e32 v189, 0xffff0000, v189
	v_lshlrev_b32_e32 v234, 16, v184
	v_and_b32_e32 v235, 0xffff0000, v184
	v_lshlrev_b32_e32 v236, 16, v185
	v_and_b32_e32 v237, 0xffff0000, v185
	v_pk_mul_f32 v[190:191], v[198:199], v[194:195]
	v_lshlrev_b32_e32 v194, 16, v186
	v_and_b32_e32 v195, 0xffff0000, v186
	v_lshlrev_b32_e32 v186, 16, v187
	v_and_b32_e32 v187, 0xffff0000, v187
	v_pk_add_f32 v[184:185], v[234:235], v[196:197]
	v_pk_add_f32 v[188:189], v[236:237], v[188:189]
	v_pk_fma_f32 v[184:185], v[184:185], 0.5, v[194:195] op_sel_hi:[1,0,1] neg_lo:[0,0,1] neg_hi:[0,0,1]
	v_pk_fma_f32 v[188:189], v[188:189], 0.5, v[186:187] op_sel_hi:[1,0,1] neg_lo:[0,0,1] neg_hi:[0,0,1]
	v_pk_fma_f32 v[184:185], v[44:45], v[184:185], v[194:195]
	v_pk_fma_f32 v[186:187], v[46:47], v[188:189], v[186:187]
	ds_write_b128 v228, v[56:59] offset:12288
	ds_write_b128 v228, v[64:67] offset:16384
	ds_write_b128 v228, v[60:63] offset:20480
	ds_write_b128 v228, v[184:187] offset:24576
	ds_write_b128 v228, v[198:201] offset:28672
	ds_write_b128 v228, v[190:193] offset:32768
	s_waitcnt lgkmcnt(0)
	s_barrier
	s_mov_b64 s[14:15], exec
	v_mbcnt_lo_u32_b32 v244, -1, 0
	v_mbcnt_hi_u32_b32 v244, -1, v244
	v_add_u32_e32 v245, 0xfffffe70, v227
	v_lshrrev_b32_e32 v245, 15, v245
	v_lshrrev_b32_e32 v246, 5, v226
	v_lshl_add_u32 v245, v245, 1, v246
	v_lshrrev_b32_e32 v247, 2, v245
	v_and_b32_e32 v248, 3, v245
	v_mul_u32_u24_e32 v249, 0xa000, v247
	v_add_u32_e32 v249, 0x190, v249
	v_and_b32_e32 v250, 7, v244
	v_lshrrev_b32_e32 v251, 3, v244
	v_lshl_add_u32 v234, v250, 5, v249
	v_lshl_add_u32 v245, v248, 4, v251
	v_lshl_add_u32 v235, v245, 2, v249
	v_add_u32_e32 v235, 0x6000, v235
	v_cmp_eq_u32_e64 s[12:13], 0, v250
	ds_read_b128 v[56:59], v234 offset:28672
	ds_read_b128 v[60:63], v234 offset:28688
	ds_read2_b32 v[64:65], v235 offset0:0 offset1:8
	ds_read_b128 v[184:187], v234 offset:32768
	ds_read_b128 v[188:191], v234 offset:20480
	ds_read_b128 v[192:195], v234 offset:16384
	ds_read_b128 v[196:199], v234 offset:12288
	ds_read_b32 v243, v234
	ds_read_b32 v241, v234
	s_mov_b32 s44, 0
.Lscan_loop:
	s_waitcnt lgkmcnt(6)
	v_pk_fma_f32 v[236:237], v[152:153], v[56:57], 0 op_sel_hi:[1,1,0]
	v_pk_fma_f32 v[238:239], v[160:161], v[56:57], 0 op_sel_hi:[1,1,0]
	v_pk_fma_f32 v[236:237], v[154:155], v[58:59], v[236:237]
	v_pk_fma_f32 v[238:239], v[162:163], v[58:59], v[238:239]
	v_pk_fma_f32 v[236:237], v[156:157], v[60:61], v[236:237]
	v_pk_fma_f32 v[238:239], v[164:165], v[60:61], v[238:239]
	v_pk_fma_f32 v[236:237], v[158:159], v[62:63], v[236:237]
	v_pk_fma_f32 v[238:239], v[166:167], v[62:63], v[238:239]
	v_add_f32_e32 v97, v236, v237
	v_add_f32_e32 v104, v238, v239
	ds_read_b128 v[168:171], v234 offset:32784
	ds_read_b128 v[172:175], v234 offset:20496
	ds_read_b128 v[176:179], v234 offset:16400
	ds_read_b128 v[180:183], v234 offset:12304
	v_add_f32_dpp v240, v97, v97 quad_perm:[1,0,3,2] row_mask:0xf bank_mask:0xf bound_ctrl:1
	v_add_f32_dpp v242, v104, v104 quad_perm:[1,0,3,2] row_mask:0xf bank_mask:0xf bound_ctrl:1
	s_nop 0
	v_add_f32_dpp v97, v240, v240 quad_perm:[2,3,0,1] row_mask:0xf bank_mask:0xf bound_ctrl:1
	v_add_f32_dpp v104, v242, v242 quad_perm:[2,3,0,1] row_mask:0xf bank_mask:0xf bound_ctrl:1
	s_nop 0
	v_add_f32_dpp v240, v97, v97 row_half_mirror row_mask:0xf bank_mask:0xf bound_ctrl:1
	v_add_f32_dpp v242, v104, v104 row_half_mirror row_mask:0xf bank_mask:0xf bound_ctrl:1
	s_nop 0
	s_waitcnt lgkmcnt(6)
; __device__ __forceinline__ void rwkv_phase(const Params& p, int ei, char* smem) {
;     ...
;           const float v0 = sOR[3072 + st * 64 + rowv], v1 = sOR[3072 + st * 64 + rowv + 16];
;           float sa0 = 0.f, sa0b = 0.f, sa1 = 0.f, sa1b = 0.f;
; #pragma unroll
;           for (int j = 0; j < 16; j += 2) {
;             sa0 += S0[j] * kkv[j]; sa0b += S0[j + 1] * kkv[j + 1];
;             sa1 += S1[j] * kkv[j]; sa1b += S1[j + 1] * kkv[j + 1];
;           }
;           sa0 += sa0b; sa1 += sa1b;
;           quad_sum2(sa0, sa1);
;           float o0 = 0.f, o0b = 0.f, o1 = 0.f, o1b = 0.f;
; #pragma unroll
;           for (int j = 0; j < 16; j += 2) {
;             S0[j] = S0[j] * wvv[j] + (v0 * ktv[j] - sa0 * akv[j]);
;             S0[j + 1] = S0[j + 1] * wvv[j + 1] + (v0 * ktv[j + 1] - sa0 * akv[j + 1]);
;             S1[j] = S1[j] * wvv[j] + (v1 * ktv[j] - sa1 * akv[j]);
;             S1[j + 1] = S1[j + 1] * wvv[j + 1] + (v1 * ktv[j + 1] - sa1 * akv[j + 1]);
;             o0 += S0[j] * rv[j]; o0b += S0[j + 1] * rv[j + 1];
;             o1 += S1[j] * rv[j]; o1b += S1[j + 1] * rv[j + 1];
;           }
;           o0 += o0b; o1 += o1b;
;           quad_sum2(o0, o1);
;           if (q == 0) { sOO[st * 64 + rowv] = o0; sOO[st * 64 + rowv + 16] = o1; }
	v_pk_mul_f32 v[244:245], v[184:185], v[240:241] op_sel_hi:[1,0]
	v_pk_mul_f32 v[248:249], v[184:185], v[242:243] op_sel_hi:[1,0]
	v_pk_mul_f32 v[246:247], v[186:187], v[240:241] op_sel_hi:[1,0]
	v_pk_mul_f32 v[250:251], v[186:187], v[242:243] op_sel_hi:[1,0]
	v_pk_fma_f32 v[244:245], v[188:189], v[64:65], v[244:245] op_sel_hi:[1,0,1] neg_lo:[0,0,1] neg_hi:[0,0,1]
	v_pk_fma_f32 v[248:249], v[188:189], v[64:65], v[248:249] op_sel:[0,1,0] op_sel_hi:[1,1,1] neg_lo:[0,0,1] neg_hi:[0,0,1]
	v_pk_fma_f32 v[246:247], v[190:191], v[64:65], v[246:247] op_sel_hi:[1,0,1] neg_lo:[0,0,1] neg_hi:[0,0,1]
	v_pk_fma_f32 v[250:251], v[190:191], v[64:65], v[250:251] op_sel:[0,1,0] op_sel_hi:[1,1,1] neg_lo:[0,0,1] neg_hi:[0,0,1]
	v_pk_fma_f32 v[152:153], v[152:153], v[192:193], v[244:245]
	v_pk_fma_f32 v[160:161], v[160:161], v[192:193], v[248:249]
	v_pk_fma_f32 v[154:155], v[154:155], v[194:195], v[246:247]
	v_pk_fma_f32 v[162:163], v[162:163], v[194:195], v[250:251]
	v_pk_fma_f32 v[252:253], v[152:153], v[196:197], 0 op_sel_hi:[1,1,0]
	v_pk_fma_f32 v[200:201], v[160:161], v[196:197], 0 op_sel_hi:[1,1,0]
	v_pk_fma_f32 v[252:253], v[154:155], v[198:199], v[252:253]
	v_pk_fma_f32 v[200:201], v[162:163], v[198:199], v[200:201]
	ds_read_b128 v[56:59], v234 offset:28928
	ds_read_b128 v[60:63], v234 offset:28944
	ds_read2_b32 v[66:67], v235 offset0:64 offset1:72
	s_waitcnt lgkmcnt(3)
	v_pk_mul_f32 v[244:245], v[168:169], v[240:241] op_sel_hi:[1,0]
	v_pk_mul_f32 v[248:249], v[168:169], v[242:243] op_sel_hi:[1,0]
	v_pk_mul_f32 v[246:247], v[170:171], v[240:241] op_sel_hi:[1,0]
	v_pk_mul_f32 v[250:251], v[170:171], v[242:243] op_sel_hi:[1,0]
	v_pk_fma_f32 v[244:245], v[172:173], v[64:65], v[244:245] op_sel_hi:[1,0,1] neg_lo:[0,0,1] neg_hi:[0,0,1]
	v_pk_fma_f32 v[248:249], v[172:173], v[64:65], v[248:249] op_sel:[0,1,0] op_sel_hi:[1,1,1] neg_lo:[0,0,1] neg_hi:[0,0,1]
	v_pk_fma_f32 v[246:247], v[174:175], v[64:65], v[246:247] op_sel_hi:[1,0,1] neg_lo:[0,0,1] neg_hi:[0,0,1]
	v_pk_fma_f32 v[250:251], v[174:175], v[64:65], v[250:251] op_sel:[0,1,0] op_sel_hi:[1,1,1] neg_lo:[0,0,1] neg_hi:[0,0,1]
	v_pk_fma_f32 v[156:157], v[156:157], v[176:177], v[244:245]
	v_pk_fma_f32 v[164:165], v[164:165], v[176:177], v[248:249]
	v_pk_fma_f32 v[158:159], v[158:159], v[178:179], v[246:247]
	v_pk_fma_f32 v[166:167], v[166:167], v[178:179], v[250:251]
	v_pk_fma_f32 v[252:253], v[156:157], v[180:181], v[252:253]
	v_pk_fma_f32 v[200:201], v[164:165], v[180:181], v[200:201]
	v_pk_fma_f32 v[252:253], v[158:159], v[182:183], v[252:253]
	v_pk_fma_f32 v[200:201], v[166:167], v[182:183], v[200:201]
	v_add_f32_e32 v97, v252, v253
	v_add_f32_e32 v104, v200, v201
	ds_read_b128 v[184:187], v234 offset:33024
	ds_read_b128 v[188:191], v234 offset:20736
	ds_read_b128 v[192:195], v234 offset:16640
	ds_read_b128 v[196:199], v234 offset:12544
	v_add_f32_dpp v244, v97, v97 quad_perm:[1,0,3,2] row_mask:0xf bank_mask:0xf bound_ctrl:1
	v_add_f32_dpp v246, v104, v104 quad_perm:[1,0,3,2] row_mask:0xf bank_mask:0xf bound_ctrl:1
	s_nop 0
	v_add_f32_dpp v97, v244, v244 quad_perm:[2,3,0,1] row_mask:0xf bank_mask:0xf bound_ctrl:1
	v_add_f32_dpp v104, v246, v246 quad_perm:[2,3,0,1] row_mask:0xf bank_mask:0xf bound_ctrl:1
	s_nop 0
	v_add_f32_dpp v244, v97, v97 row_half_mirror row_mask:0xf bank_mask:0xf bound_ctrl:1
	v_add_f32_dpp v246, v104, v104 row_half_mirror row_mask:0xf bank_mask:0xf bound_ctrl:1
	s_and_saveexec_b64 s[16:17], s[12:13]
	s_nop 0
	ds_write_b32 v235, v244 offset:12288
	ds_write_b32 v235, v246 offset:12320
	s_or_b64 exec, exec, s[16:17]
	s_waitcnt lgkmcnt(6)
	v_pk_fma_f32 v[236:237], v[152:153], v[56:57], 0 op_sel_hi:[1,1,0]
	v_pk_fma_f32 v[238:239], v[160:161], v[56:57], 0 op_sel_hi:[1,1,0]
	v_pk_fma_f32 v[236:237], v[154:155], v[58:59], v[236:237]
	v_pk_fma_f32 v[238:239], v[162:163], v[58:59], v[238:239]
	v_pk_fma_f32 v[236:237], v[156:157], v[60:61], v[236:237]
	v_pk_fma_f32 v[238:239], v[164:165], v[60:61], v[238:239]
	v_pk_fma_f32 v[236:237], v[158:159], v[62:63], v[236:237]
	v_pk_fma_f32 v[238:239], v[166:167], v[62:63], v[238:239]
	v_add_f32_e32 v97, v236, v237
	v_add_f32_e32 v104, v238, v239
	ds_read_b128 v[168:171], v234 offset:33040
	ds_read_b128 v[172:175], v234 offset:20752
	ds_read_b128 v[176:179], v234 offset:16656
	ds_read_b128 v[180:183], v234 offset:12560
	v_add_f32_dpp v240, v97, v97 quad_perm:[1,0,3,2] row_mask:0xf bank_mask:0xf bound_ctrl:1
	v_add_f32_dpp v242, v104, v104 quad_perm:[1,0,3,2] row_mask:0xf bank_mask:0xf bound_ctrl:1
	s_nop 0
	v_add_f32_dpp v97, v240, v240 quad_perm:[2,3,0,1] row_mask:0xf bank_mask:0xf bound_ctrl:1
	v_add_f32_dpp v104, v242, v242 quad_perm:[2,3,0,1] row_mask:0xf bank_mask:0xf bound_ctrl:1
	s_nop 0
	v_add_f32_dpp v240, v97, v97 row_half_mirror row_mask:0xf bank_mask:0xf bound_ctrl:1
	v_add_f32_dpp v242, v104, v104 row_half_mirror row_mask:0xf bank_mask:0xf bound_ctrl:1
	s_nop 0
	s_waitcnt lgkmcnt(6)
; __device__ __forceinline__ void rwkv_phase(const Params& p, int ei, char* smem) {
;     ...
;           for (int j = 0; j < 16; j += 2) {
;             sa0 += S0[j] * kkv[j]; sa0b += S0[j + 1] * kkv[j + 1];
;             sa1 += S1[j] * kkv[j]; sa1b += S1[j + 1] * kkv[j + 1];
;           }
;           sa0 += sa0b; sa1 += sa1b;
;           quad_sum2(sa0, sa1);
;           float o0 = 0.f, o0b = 0.f, o1 = 0.f, o1b = 0.f;
; #pragma unroll
;           for (int j = 0; j < 16; j += 2) {
;             S0[j] = S0[j] * wvv[j] + (v0 * ktv[j] - sa0 * akv[j]);
;             S0[j + 1] = S0[j + 1] * wvv[j + 1] + (v0 * ktv[j + 1] - sa0 * akv[j + 1]);
;             S1[j] = S1[j] * wvv[j] + (v1 * ktv[j] - sa1 * akv[j]);
;             S1[j + 1] = S1[j + 1] * wvv[j + 1] + (v1 * ktv[j + 1] - sa1 * akv[j + 1]);
;             o0 += S0[j] * rv[j]; o0b += S0[j + 1] * rv[j + 1];
;             o1 += S1[j] * rv[j]; o1b += S1[j + 1] * rv[j + 1];
;           }
;           o0 += o0b; o1 += o1b;
;           quad_sum2(o0, o1);
;           if (q == 0) { sOO[st * 64 + rowv] = o0; sOO[st * 64 + rowv + 16] = o1; }
	v_pk_mul_f32 v[244:245], v[184:185], v[240:241] op_sel_hi:[1,0]
	v_pk_mul_f32 v[248:249], v[184:185], v[242:243] op_sel_hi:[1,0]
	v_pk_mul_f32 v[246:247], v[186:187], v[240:241] op_sel_hi:[1,0]
	v_pk_mul_f32 v[250:251], v[186:187], v[242:243] op_sel_hi:[1,0]
	v_pk_fma_f32 v[244:245], v[188:189], v[66:67], v[244:245] op_sel_hi:[1,0,1] neg_lo:[0,0,1] neg_hi:[0,0,1]
	v_pk_fma_f32 v[248:249], v[188:189], v[66:67], v[248:249] op_sel:[0,1,0] op_sel_hi:[1,1,1] neg_lo:[0,0,1] neg_hi:[0,0,1]
	v_pk_fma_f32 v[246:247], v[190:191], v[66:67], v[246:247] op_sel_hi:[1,0,1] neg_lo:[0,0,1] neg_hi:[0,0,1]
	v_pk_fma_f32 v[250:251], v[190:191], v[66:67], v[250:251] op_sel:[0,1,0] op_sel_hi:[1,1,1] neg_lo:[0,0,1] neg_hi:[0,0,1]
	v_pk_fma_f32 v[152:153], v[152:153], v[192:193], v[244:245]
	v_pk_fma_f32 v[160:161], v[160:161], v[192:193], v[248:249]
	v_pk_fma_f32 v[154:155], v[154:155], v[194:195], v[246:247]
	v_pk_fma_f32 v[162:163], v[162:163], v[194:195], v[250:251]
	v_pk_fma_f32 v[252:253], v[152:153], v[196:197], 0 op_sel_hi:[1,1,0]
	v_pk_fma_f32 v[200:201], v[160:161], v[196:197], 0 op_sel_hi:[1,1,0]
	v_pk_fma_f32 v[252:253], v[154:155], v[198:199], v[252:253]
	v_pk_fma_f32 v[200:201], v[162:163], v[198:199], v[200:201]
	ds_read_b128 v[56:59], v234 offset:29184
	ds_read_b128 v[60:63], v234 offset:29200
	ds_read2_b32 v[64:65], v235 offset0:128 offset1:136
	s_waitcnt lgkmcnt(3)
	v_pk_mul_f32 v[244:245], v[168:169], v[240:241] op_sel_hi:[1,0]
	v_pk_mul_f32 v[248:249], v[168:169], v[242:243] op_sel_hi:[1,0]
	v_pk_mul_f32 v[246:247], v[170:171], v[240:241] op_sel_hi:[1,0]
	v_pk_mul_f32 v[250:251], v[170:171], v[242:243] op_sel_hi:[1,0]
	v_pk_fma_f32 v[244:245], v[172:173], v[66:67], v[244:245] op_sel_hi:[1,0,1] neg_lo:[0,0,1] neg_hi:[0,0,1]
	v_pk_fma_f32 v[248:249], v[172:173], v[66:67], v[248:249] op_sel:[0,1,0] op_sel_hi:[1,1,1] neg_lo:[0,0,1] neg_hi:[0,0,1]
	v_pk_fma_f32 v[246:247], v[174:175], v[66:67], v[246:247] op_sel_hi:[1,0,1] neg_lo:[0,0,1] neg_hi:[0,0,1]
	v_pk_fma_f32 v[250:251], v[174:175], v[66:67], v[250:251] op_sel:[0,1,0] op_sel_hi:[1,1,1] neg_lo:[0,0,1] neg_hi:[0,0,1]
	v_pk_fma_f32 v[156:157], v[156:157], v[176:177], v[244:245]
	v_pk_fma_f32 v[164:165], v[164:165], v[176:177], v[248:249]
	v_pk_fma_f32 v[158:159], v[158:159], v[178:179], v[246:247]
	v_pk_fma_f32 v[166:167], v[166:167], v[178:179], v[250:251]
	v_pk_fma_f32 v[252:253], v[156:157], v[180:181], v[252:253]
	v_pk_fma_f32 v[200:201], v[164:165], v[180:181], v[200:201]
	v_pk_fma_f32 v[252:253], v[158:159], v[182:183], v[252:253]
	v_pk_fma_f32 v[200:201], v[166:167], v[182:183], v[200:201]
	v_add_f32_e32 v97, v252, v253
	v_add_f32_e32 v104, v200, v201
	ds_read_b128 v[184:187], v234 offset:33280
	ds_read_b128 v[188:191], v234 offset:20992
	ds_read_b128 v[192:195], v234 offset:16896
	ds_read_b128 v[196:199], v234 offset:12800
	v_add_f32_dpp v244, v97, v97 quad_perm:[1,0,3,2] row_mask:0xf bank_mask:0xf bound_ctrl:1
	v_add_f32_dpp v246, v104, v104 quad_perm:[1,0,3,2] row_mask:0xf bank_mask:0xf bound_ctrl:1
	s_nop 0
	v_add_f32_dpp v97, v244, v244 quad_perm:[2,3,0,1] row_mask:0xf bank_mask:0xf bound_ctrl:1
	v_add_f32_dpp v104, v246, v246 quad_perm:[2,3,0,1] row_mask:0xf bank_mask:0xf bound_ctrl:1
	s_nop 0
	v_add_f32_dpp v244, v97, v97 row_half_mirror row_mask:0xf bank_mask:0xf bound_ctrl:1
	v_add_f32_dpp v246, v104, v104 row_half_mirror row_mask:0xf bank_mask:0xf bound_ctrl:1
	s_and_saveexec_b64 s[16:17], s[12:13]
	s_nop 0
	ds_write_b32 v235, v244 offset:12544
	ds_write_b32 v235, v246 offset:12576
	s_or_b64 exec, exec, s[16:17]
	v_add_u32_e32 v234, 0x200, v234
	v_add_u32_e32 v235, 0x200, v235
	s_add_i32 s44, s44, 2
	s_cmp_lg_u32 s44, 16
	s_cbranch_scc1 .Lscan_loop
	s_branch .LBB0_838

; __global__ void __launch_bounds__(NTHR) fwd_megakernel(Params p) {
;   extern __shared__ __attribute__((aligned(16))) char smem[];
;   cg::grid_group grid = cg::this_grid();
;   if (threadIdx.x == 0) {
; #pragma unroll
;     for (int i = 0; i < 39; ++i) s_ptab[i] = (unsigned long long)p.in[i];
;     s_ptab[39] = (unsigned long long)p.out;
;     s_ptab[40] = (unsigned long long)p.ws;
;   }
;   __syncthreads();
;     ...
;   prep_phase(p, smem);
;   grid.sync();
; #pragma unroll 1
;   for (int layer = 0; layer < 4; ++layer) {
;     const int hi = layer >> 1;
;     const bool last = (layer == 3);
;     const bool even = (layer & 1) == 0;
; #pragma unroll 1
;     for (int ph = (layer == 0 ? 0 : 1); ph < 8; ++ph) {
;       char* ws = (char*)ldptr(40);
;       switch (ph) {
;         case 0:
;           modulate_phase(p, layer, 0, false, true);
;           break;
;         case 1:
;           if (layer > 0) {
;             convert_fp8(ldptr(I_PU) + (size_t)layer * 16384 * 1024, (unsigned char*)(ws + OFF_PU), (size_t)16384 * 1024, 64.f);
;             convert_fp8(ldptr(I_PV) + (size_t)layer * 16384 * 1024, (unsigned char*)(ws + OFF_PV), (size_t)16384 * 1024, 8.f);
;           }
;           if (even) gemm_store_phase(p, (const u16*)(ws + OFF_WIN) + (size_t)hi * 2944 * 1024, 23, PSTR, smem);
;           else gemm_store_phase(p, (const u16*)(ws + OFF_WQKV) + (size_t)hi * 3072 * 1024, 24, QSTR, smem);
;           break;
;         case 2:
;           if (even) { rwkv_phase(p, hi, smem); lru_phase(p, hi, smem); }
;           else qknorm_phase(p, hi, smem);
;           break;
;         case 3:
;           if (even) even_post_phase(p, hi, smem);
;           else attn_phase(p, layer, smem);
;           break;
;         case 4:
;           if (even) gemm_resid_phase(p, layer, (const u16*)(ws + OFF_ACT), (const u16*)(ws + OFF_WOUT) + (size_t)hi * 1024 * 1024, false, layer == 0, smem);
;           else gemm_resid_phase(p, layer, (const u16*)(ws + OFF_R + 2 * RQ), (const u16*)(ws + OFF_WO) + (size_t)hi * 1024 * 1024, last, false, smem);
;           break;
;         case 5:
;           modulate_phase(p, layer, 1, last, false);
;           break;
;         case 6:
;           peer_score_phase(p, layer, last, smem);
;           break;
;         default:
;           peer_gather_phase(p, layer, last, smem, !last);
;           break;
;       }
;       xcd_barrier(xb);
;     }
;   }
; }
	.amdhsa_kernel _Z14fwd_megakernel6Params
		.amdhsa_group_segment_fixed_size 400
		.amdhsa_private_segment_fixed_size 0
		.amdhsa_kernarg_size 584
		.amdhsa_user_sgpr_count 2
		.amdhsa_user_sgpr_dispatch_ptr 0
		.amdhsa_user_sgpr_queue_ptr 0
		.amdhsa_user_sgpr_kernarg_segment_ptr 1
		.amdhsa_user_sgpr_dispatch_id 0
		.amdhsa_user_sgpr_kernarg_preload_length 0
		.amdhsa_user_sgpr_kernarg_preload_offset 0
		.amdhsa_user_sgpr_private_segment_size 0
		.amdhsa_uses_dynamic_stack 0
		.amdhsa_enable_private_segment 0
		.amdhsa_system_sgpr_workgroup_id_x 1
		.amdhsa_system_sgpr_workgroup_id_y 0
		.amdhsa_system_sgpr_workgroup_id_z 0
		.amdhsa_system_sgpr_workgroup_info 0
		.amdhsa_system_vgpr_workitem_id 2
		.amdhsa_next_free_vgpr 255
		.amdhsa_next_free_sgpr 98
		.amdhsa_accum_offset 256
		.amdhsa_reserve_vcc 1
		.amdhsa_float_round_mode_32 0
		.amdhsa_float_round_mode_16_64 0
		.amdhsa_float_denorm_mode_32 3
		.amdhsa_float_denorm_mode_16_64 3
		.amdhsa_dx10_clamp 1
		.amdhsa_ieee_mode 1
		.amdhsa_fp16_overflow 0
		.amdhsa_tg_split 0
		.amdhsa_exception_fp_ieee_invalid_op 0
		.amdhsa_exception_fp_denorm_src 0
		.amdhsa_exception_fp_ieee_div_zero 0
		.amdhsa_exception_fp_ieee_overflow 0
		.amdhsa_exception_fp_ieee_underflow 0
		.amdhsa_exception_fp_ieee_inexact 0
		.amdhsa_exception_int_div_zero 0
	.end_amdhsa_kernel

; __global__ void __launch_bounds__(NTHR) fwd_megakernel(Params p) {
;   extern __shared__ __attribute__((aligned(16))) char smem[];
;   cg::grid_group grid = cg::this_grid();
amdhsa.kernels:
  - .agpr_count:     0
    .args:
      - .offset:         0
        .size:           328
        .value_kind:     by_value
      - .offset:         328
        .size:           4
        .value_kind:     hidden_block_count_x
      - .offset:         332
        .size:           4
        .value_kind:     hidden_block_count_y
      - .offset:         336
        .size:           4
        .value_kind:     hidden_block_count_z
      - .offset:         340
        .size:           2
        .value_kind:     hidden_group_size_x
      - .offset:         342
        .size:           2
        .value_kind:     hidden_group_size_y
      - .offset:         344
        .size:           2
        .value_kind:     hidden_group_size_z
      - .offset:         346
        .size:           2
        .value_kind:     hidden_remainder_x
      - .offset:         348
        .size:           2
        .value_kind:     hidden_remainder_y
      - .offset:         350
        .size:           2
        .value_kind:     hidden_remainder_z
      - .offset:         368
        .size:           8
        .value_kind:     hidden_global_offset_x
      - .offset:         376
        .size:           8
        .value_kind:     hidden_global_offset_y
      - .offset:         384
        .size:           8
        .value_kind:     hidden_global_offset_z
      - .offset:         392
        .size:           2
        .value_kind:     hidden_grid_dims
      - .offset:         416
        .size:           8
        .value_kind:     hidden_multigrid_sync_arg
      - .offset:         448
        .size:           4
        .value_kind:     hidden_dynamic_lds_size
    .group_segment_fixed_size: 400
    .kernarg_segment_align: 8
    .kernarg_segment_size: 584
    .language:       OpenCL C
    .language_version:
      - 2
      - 0
    .max_flat_workgroup_size: 512
    .name:           _Z14fwd_megakernel6Params
    .private_segment_fixed_size: 0
    .sgpr_count:     104
    .sgpr_spill_count: 62
    .symbol:         _Z14fwd_megakernel6Params.kd
    .uniform_work_group_size: 1
    .uses_dynamic_stack: false
    .vgpr_count:     255
    .vgpr_spill_count: 0
    .wavefront_size: 64
